# static wave priority for waves 4-7 raised from 1 to 3
# baseline (speedup 1.0000x reference)
; DI int half_id() { return __builtin_amdgcn_readfirstlane((int)(threadIdx.x >> 8)); }
; #define LAS __attribute__((address_space(3)))
; __global__ void __launch_bounds__(512) fwd_megakernel(Params p) {
;   extern __shared__ __attribute__((aligned(16))) char smem[];
;   cg::grid_group grid = cg::this_grid();
;   __shared__ uint4 xb_words;
;   if (threadIdx.x == 0) {
;     xb_words = make_uint4(0u, 0u, 0u, 0u);
;     hsync_impl(true);
;   }
;   __syncthreads();
;   if (p.ws == nullptr) grid.sync();
;   XcdBarrier xb = xcd_barrier_post((unsigned*)(p.ws + WS_BAR), (volatile LAS unsigned*)&xb_words);
;   char* hsm = smem + half_id() * HALF_LDS;
_Z14fwd_megakernel6Params:
	v_readfirstlane_b32 s3, v0
	s_nop 3
	s_and_b32 s3, s3, 0x3ff
	s_cmp_ge_u32 s3, 256
	s_cbranch_scc0 .Lprio_done
	s_setprio 3
